# grid barrier: non-leader workgroups issue their L1 invalidate (buffer_inv sc1) on arrival, overlapping the wait, instead of after the release flag
# speedup vs baseline: 1.0855x; 1.0151x over previous
.LBB0_598:
	s_or_b64 exec, exec, s[2:3]
	v_cvt_f32_u32_e32 v4, v2
	s_waitcnt vmcnt(0)
	v_readfirstlane_b32 s2, v3
	v_sub_u32_e32 v3, 0, v2
	v_rcp_iflag_f32_e32 v4, v4
	v_add_u32_e32 v5, s2, v1
	v_mul_f32_e32 v4, 0x4f7ffffe, v4
	v_cvt_u32_f32_e32 v4, v4
	v_mul_lo_u32 v1, v3, v4
	v_mul_hi_u32 v1, v4, v1
	v_add_u32_e32 v1, v4, v1
	v_mul_hi_u32 v1, v5, v1
	v_mul_lo_u32 v3, v1, v2
	v_sub_u32_e32 v3, v5, v3
	v_add_u32_e32 v4, 1, v1
	v_cmp_ge_u32_e32 vcc, v3, v2
	s_nop 1
	v_cndmask_b32_e32 v1, v1, v4, vcc
	v_sub_u32_e32 v4, v3, v2
	v_cndmask_b32_e32 v3, v3, v4, vcc
	v_add_u32_e32 v4, 1, v1
	v_cmp_ge_u32_e32 vcc, v3, v2
	v_add_u32_e32 v3, 1, v5
	s_nop 0
	v_cndmask_b32_e32 v1, v1, v4, vcc
	v_mul_lo_u32 v4, v2, v1
	v_add_u32_e32 v2, v4, v2
	v_cmp_ne_u32_e32 vcc, v3, v2
	s_and_saveexec_b64 s[2:3], vcc
	s_xor_b64 s[2:3], exec, s[2:3]
	s_cbranch_execz .LBB0_612
	buffer_inv sc1
	v_readlane_b32 s6, v255, 30
	v_readlane_b32 s7, v255, 31
	s_waitcnt lgkmcnt(0)
	s_nop 3
	global_load_dword v0, v177, s[6:7] sc1
	s_waitcnt vmcnt(0)
	v_cmp_eq_u32_e32 vcc, v0, v1
	s_and_saveexec_b64 s[6:7], vcc
	s_cbranch_execz .LBB0_611
	s_mov_b32 s12, 1
	s_mov_b64 s[8:9], 0
	s_branch .LBB0_602

.LBB0_611:
	s_or_b64 exec, exec, s[6:7]
	s_waitcnt vmcnt(0)
.LBB0_612:
	s_andn2_saveexec_b64 s[2:3], s[2:3]
	s_cbranch_execz .LBB0_22
	s_mov_b64 s[2:3], exec
	buffer_wbl2 sc1
	s_waitcnt lgkmcnt(0)
	s_waitcnt vmcnt(0)
	v_mbcnt_lo_u32_b32 v1, s2, 0
	v_mbcnt_hi_u32_b32 v1, s3, v1
	v_cmp_eq_u32_e32 vcc, 0, v1
	s_and_saveexec_b64 s[6:7], vcc
	s_cbranch_execz .LBB0_615
	s_bcnt1_i32_b64 s2, s[2:3]
	v_mov_b32_e32 v2, s2
	v_readlane_b32 s2, v255, 32
	v_readlane_b32 s3, v255, 33
	s_nop 4
	global_atomic_add v2, v177, v2, s[2:3] sc0
